# baseline (speedup 1.0000x reference)
; DI float h2lo(unsigned u) { return (float)__builtin_bit_cast(f16x2_t, u)[0]; }
; DI float h2hi(unsigned u) { return (float)__builtin_bit_cast(f16x2_t, u)[1]; }
; DI int my_tid() { int t = tid_raw(); asm volatile("" : "+v"(t)); return t; }
; DI float shfl_xor_l(float v, int mask, int lane) { return __int_as_float(__builtin_amdgcn_ds_bpermute((lane ^ mask) << 2, __float_as_int(v))); }
; DI void ln_phase(const Params& p, const u16* src, const float* g, const float* b, float* dstf, u16* dstb) {
;   const int lane = my_tid() & 63, wid = my_tid() >> 6;
;   const int stride = gridDim.x * 8;
;   int row = blockIdx.x * 8 + wid;
;   u32x2 raw[4], nxt[4];
;   f32x4 gv[4], bv[4];
; #pragma unroll
;   for (int i = 0; i < 4; ++i) { gv[i] = *(const f32x4*)(g + i * 256 + lane * 4); bv[i] = *(const f32x4*)(b + i * 256 + lane * 4); }
;   if (row < S) {
; #pragma unroll
;     for (int i = 0; i < 4; ++i) raw[i] = *(const u32x2*)(src + (size_t)row * D + i * 256 + lane * 4);
;   }
;   for (; row < S; row += stride) {
;     const int rn = row + stride;
;     if (rn < S) {
; #pragma unroll
;       for (int i = 0; i < 4; ++i) nxt[i] = *(const u32x2*)(src + (size_t)rn * D + i * 256 + lane * 4);
;     }
;     f32x4 v[4];
;     float s = 0.f;
; #pragma unroll
;     for (int i = 0; i < 4; ++i) { v[i] = (f32x4){h2lo(raw[i][0]), h2hi(raw[i][0]), h2lo(raw[i][1]), h2hi(raw[i][1])}; s += (v[i][0] + v[i][1]) + (v[i][2] + v[i][3]); }
; #pragma unroll
;     for (int o = 32; o >= 1; o >>= 1) s += shfl_xor_l(s, o, lane);
.LBB0_1109:
	s_movk_i32 s59, 0x3c0
	s_movk_i32 s58, 0x3000
	s_or_b64 exec, exec, s[8:9]
	s_waitcnt lgkmcnt(0)
	s_barrier
	s_getreg_b32 s2, hwreg(HW_REG_HW_ID, 0, 6)
	s_lshl_b32 s2, s2, 2
	s_and_b32 s2, s2, 0xfc
	s_add_i32 s2, s2, 0x20040
	v_mov_b32_e32 v0, s2
	ds_read_b32 v0, v0
	s_lshl_b32 s92, s69, 10
	s_waitcnt lgkmcnt(0)
	v_readfirstlane_b32 s2, v0
	s_nop 1
	v_lshl_or_b32 v34, s2, 6, v214
	s_getreg_b32 s2, hwreg(HW_REG_HW_ID, 0, 6)
	s_lshl_b32 s2, s2, 2
	s_and_b32 s2, s2, 0xfc
	s_add_i32 s2, s2, 0x20040
	v_mov_b32_e32 v0, s2
	ds_read_b32 v0, v0
	s_waitcnt lgkmcnt(0)
	v_readfirstlane_b32 s2, v0
	s_nop 1
	v_lshl_or_b32 v0, s2, 6, v214
	v_readlane_b32 s2, v255, 12
	v_ashrrev_i32_e32 v36, 6, v0
	s_nop 0
	v_add_u32_e32 v32, s2, v36
	s_movk_i32 s2, 0x4000
	v_cmp_gt_i32_e32 vcc, s2, v32
	s_and_saveexec_b64 s[8:9], vcc
	s_cbranch_execz .LBB0_1114
	s_lshl_b64 s[2:3], s[92:93], 2
	v_readlane_b32 s36, v252, 18
	v_readlane_b32 s37, v252, 19
	s_add_u32 s22, s36, s2
	v_readlane_b32 s38, v252, 20
	s_addc_u32 s23, s37, s3
	v_lshlrev_b32_e32 v35, 2, v34
	v_readlane_b32 s39, v252, 21
	s_add_u32 s2, s38, s2
	v_and_b32_e32 v37, 0xfc, v35
	s_addc_u32 s3, s39, s3
	v_lshlrev_b32_e32 v28, 2, v37
	global_load_dwordx4 v[0:3], v28, s[22:23]
	global_load_dwordx4 v[4:7], v28, s[22:23] offset:1024
	global_load_dwordx4 v[8:11], v28, s[2:3]
	global_load_dwordx4 v[12:15], v28, s[2:3] offset:1024
	global_load_dwordx4 v[16:19], v28, s[22:23] offset:2048
	global_load_dwordx4 v[20:23], v28, s[22:23] offset:3072
	global_load_dwordx4 v[24:27], v28, s[2:3] offset:2048
	s_nop 0
	global_load_dwordx4 v[28:31], v28, s[2:3] offset:3072
	v_ashrrev_i32_e32 v33, 31, v32
	v_readlane_b32 s2, v254, 14
	v_lshlrev_b64 v[38:39], 11, v[32:33]
	v_readlane_b32 s3, v254, 15
	v_lshlrev_b32_e32 v64, 1, v37
	v_bfrev_b32_e32 v37, 0.5
	v_lshl_add_u64 v[40:41], s[2:3], 0, v[38:39]
	v_lshl_add_u64 v[40:41], v[40:41], 0, v[64:65]
	v_lshl_add_u64 v[82:83], v[40:41], 0, v[64:65]
	v_readfirstlane_b32 s100, v36
	v_readlane_b32 s101, v255, 14
	s_lshl_b32 s100, s100, 14
	s_nop 0
	v_mov_b32_e32 v86, s101
	v_readlane_b32 s101, v255, 15
	v_add_u32_e32 v84, s100, v64
	s_nop 1
	v_mov_b32_e32 v87, s101
	s_mov_b32 m0, s100
	s_nop 0
	global_load_lds_dwordx4 v[82:83], off
	global_load_lds_dwordx4 v[82:83], off offset:1024
	v_lshl_add_u64 v[82:83], v[82:83], 0, v[86:87]
	s_add_u32 s100, s100, 0x800
	s_mov_b32 m0, s100
	s_nop 0
	global_load_lds_dwordx4 v[82:83], off
	global_load_lds_dwordx4 v[82:83], off offset:1024
	v_lshl_add_u64 v[82:83], v[82:83], 0, v[86:87]
	s_add_u32 s100, s100, 0x800
	s_mov_b32 m0, s100
	s_nop 0
	global_load_lds_dwordx4 v[82:83], off
	global_load_lds_dwordx4 v[82:83], off offset:1024
	v_lshl_add_u64 v[82:83], v[82:83], 0, v[86:87]
	s_add_u32 s100, s100, 0x800
	s_mov_b32 m0, s100
	s_nop 0
	global_load_lds_dwordx4 v[82:83], off
	global_load_lds_dwordx4 v[82:83], off offset:1024
	v_lshl_add_u64 v[82:83], v[82:83], 0, v[86:87]
	s_add_u32 s100, s100, 0x800
	s_mov_b32 m0, s100
	s_nop 0
	global_load_lds_dwordx4 v[82:83], off
	global_load_lds_dwordx4 v[82:83], off offset:1024
	v_lshl_add_u64 v[82:83], v[82:83], 0, v[86:87]
	s_add_u32 s100, s100, 0x800
	s_mov_b32 m0, s100
	s_nop 0
	global_load_lds_dwordx4 v[82:83], off
	global_load_lds_dwordx4 v[82:83], off offset:1024
	v_lshl_add_u64 v[82:83], v[82:83], 0, v[86:87]
	s_add_u32 s100, s100, 0x800
	s_mov_b32 m0, s100
	s_nop 0
	global_load_lds_dwordx4 v[82:83], off
	global_load_lds_dwordx4 v[82:83], off offset:1024
	v_lshl_add_u64 v[82:83], v[82:83], 0, v[86:87]
	s_add_u32 s100, s100, 0x800
	s_mov_b32 m0, s100
	s_nop 0
	global_load_lds_dwordx4 v[82:83], off
	global_load_lds_dwordx4 v[82:83], off offset:1024
	s_movk_i32 s2, 0x80
	v_bitop3_b32 v33, v35, s2, v37 bitop3:0x6c
	v_readlane_b32 s2, v255, 13
	v_bitop3_b32 v54, v35, 64, v37 bitop3:0x6c
	v_bitop3_b32 v55, v35, 32, v37 bitop3:0x6c
	v_add_u32_e32 v36, s2, v36
	v_bitop3_b32 v56, v35, 16, v37 bitop3:0x6c
	v_bitop3_b32 v57, v35, 8, v37 bitop3:0x6c
	v_bitop3_b32 v58, v35, 4, v37 bitop3:0x6c
	v_and_b32_e32 v34, 63, v34
	v_ashrrev_i32_e32 v37, 31, v36
	v_lshlrev_b32_e32 v64, 3, v34
	v_lshl_add_u64 v[34:35], s[90:91], 0, v[38:39]
	v_lshlrev_b64 v[36:37], 11, v[36:37]
	v_mov_b32_e32 v38, 0
	v_lshl_add_u64 v[36:37], s[90:91], 0, v[36:37]
	s_mov_b64 s[22:23], 0
	v_mov_b32_e32 v39, v38
	v_mov_b32_e32 v40, v38
	v_mov_b32_e32 v41, v38
	v_mov_b32_e32 v42, v38
	v_mov_b32_e32 v43, v38
	v_mov_b32_e32 v44, v38
	v_mov_b32_e32 v45, v38
	v_readlane_b32 s40, v252, 22
	v_readlane_b32 s41, v252, 23
	v_readlane_b32 s42, v252, 24
	v_readlane_b32 s43, v252, 25
	v_readlane_b32 s44, v252, 26
	v_readlane_b32 s45, v252, 27
	v_readlane_b32 s46, v252, 28
	v_readlane_b32 s47, v252, 29
	v_readlane_b32 s48, v252, 30
	v_readlane_b32 s49, v252, 31
	v_readlane_b32 s50, v252, 32
	v_readlane_b32 s51, v252, 33
	s_waitcnt vmcnt(0)
	s_branch .LBB0_1112
; DI float h2lo(unsigned u) { return (float)__builtin_bit_cast(f16x2_t, u)[0]; }
; DI float h2hi(unsigned u) { return (float)__builtin_bit_cast(f16x2_t, u)[1]; }
; DI float shfl_xor_l(float v, int mask, int lane) { return __int_as_float(__builtin_amdgcn_ds_bpermute((lane ^ mask) << 2, __float_as_int(v))); }
; DI void ln_phase(const Params& p, const u16* src, const float* g, const float* b, float* dstf, u16* dstb) {
;     ...
;   for (; row < S; row += stride) {
;     const int rn = row + stride;
;     if (rn < S) {
; #pragma unroll
;       for (int i = 0; i < 4; ++i) nxt[i] = *(const u32x2*)(src + (size_t)rn * D + i * 256 + lane * 4);
;     }
;     f32x4 v[4];
;     float s = 0.f;
; #pragma unroll
;     for (int i = 0; i < 4; ++i) { v[i] = (f32x4){h2lo(raw[i][0]), h2hi(raw[i][0]), h2lo(raw[i][1]), h2hi(raw[i][1])}; s += (v[i][0] + v[i][1]) + (v[i][2] + v[i][3]); }
; #pragma unroll
;     for (int o = 32; o >= 1; o >>= 1) s += shfl_xor_l(s, o, lane);
;     const float mu = s * (1.0f / 1024.0f);
;     float q = 0.f;
; #pragma unroll
;     for (int i = 0; i < 4; ++i) { v[i] = v[i] - mu; q += (v[i][0] * v[i][0] + v[i][1] * v[i][1]) + (v[i][2] * v[i][2] + v[i][3] * v[i][3]); }
.LBB0_1111:
	s_or_b64 exec, exec, s[28:29]
	ds_read_b64 v[52:53], v84
	ds_read_b64 v[50:51], v84 offset:512
	ds_read_b64 v[48:49], v84 offset:1024
	ds_read_b64 v[46:47], v84 offset:1536
	v_add_u32_e32 v84, 0x800, v84
	s_waitcnt lgkmcnt(0)
	v_cvt_f32_f16_sdwa v60, v52 dst_sel:DWORD dst_unused:UNUSED_PAD src0_sel:WORD_1
	v_cvt_f32_f16_e32 v62, v52
	v_cvt_f32_f16_sdwa v61, v53 dst_sel:DWORD dst_unused:UNUSED_PAD src0_sel:WORD_1
	v_cvt_f32_f16_e32 v63, v53
	v_cvt_f32_f16_e32 v66, v50
	v_cvt_f32_f16_e32 v67, v51
	v_cvt_f32_f16_sdwa v68, v46 dst_sel:DWORD dst_unused:UNUSED_PAD src0_sel:WORD_1
	v_pk_add_f32 v[60:61], v[62:63], v[60:61]
	v_cvt_f32_f16_sdwa v62, v50 dst_sel:DWORD dst_unused:UNUSED_PAD src0_sel:WORD_1
	v_cvt_f32_f16_sdwa v63, v51 dst_sel:DWORD dst_unused:UNUSED_PAD src0_sel:WORD_1
	v_add_f32_e32 v59, v60, v61
	v_add_f32_e32 v61, 0, v59
	v_cvt_f32_f16_sdwa v59, v48 dst_sel:DWORD dst_unused:UNUSED_PAD src0_sel:WORD_1
	v_pk_add_f32 v[62:63], v[66:67], v[62:63]
	v_cvt_f32_f16_e32 v60, v48
	v_pk_add_f32 v[62:63], v[62:63], v[62:63] op_sel_hi:[0,1]
	v_cvt_f32_f16_sdwa v62, v49 dst_sel:DWORD dst_unused:UNUSED_PAD src0_sel:WORD_1
	v_cvt_f32_f16_e32 v66, v49
	v_add_f32_e32 v67, v60, v59
	v_cvt_f32_f16_sdwa v60, v47 dst_sel:DWORD dst_unused:UNUSED_PAD src0_sel:WORD_1
	s_and_b64 s[2:3], exec, s[38:39]
	v_add_f32_e32 v69, v66, v62
	v_cvt_f32_f16_e32 v66, v46
	v_cvt_f32_f16_e32 v62, v47
	s_or_b64 s[22:23], s[2:3], s[22:23]
	v_pk_add_f32 v[66:67], v[66:67], v[68:69]
	v_pk_add_f32 v[60:61], v[62:63], v[60:61]
	s_nop 0
	v_pk_add_f32 v[60:61], v[66:67], v[60:61]
	s_nop 0
	v_add_f32_e32 v59, v60, v61
	s_nop 1
	v_add_f32_dpp v59, v59, v59 quad_perm:[1,0,3,2] row_mask:0xf bank_mask:0xf
	s_nop 1
	v_add_f32_dpp v59, v59, v59 quad_perm:[2,3,0,1] row_mask:0xf bank_mask:0xf
	s_nop 1
	v_add_f32_dpp v59, v59, v59 row_half_mirror row_mask:0xf bank_mask:0xf
	s_nop 1
	v_add_f32_dpp v59, v59, v59 row_mirror row_mask:0xf bank_mask:0xf
	v_mov_b32_e32 v60, v59
	s_nop 1
	v_permlane16_swap_b32 v60, v59
	v_add_f32_e32 v59, v59, v60
	v_mov_b32_e32 v60, v59
	s_nop 1
	v_permlane32_swap_b32 v60, v59
	v_add_f32_e32 v59, v59, v60
	v_fma_mix_f32 v61, v59, s65, v52 op_sel:[0,0,1] op_sel_hi:[0,0,1]
	v_fma_mix_f32 v60, v59, s65, v52 op_sel_hi:[0,0,1]
	v_fma_mix_f32 v63, v59, s65, v53 op_sel:[0,0,1] op_sel_hi:[0,0,1]
	v_fma_mix_f32 v62, v59, s65, v53 op_sel_hi:[0,0,1]
	v_pk_mul_f32 v[52:53], v[62:63], v[62:63]
	v_pk_mul_f32 v[66:67], v[60:61], v[60:61]
	v_fma_mix_f32 v77, v59, s65, v47 op_sel:[0,0,1] op_sel_hi:[0,0,1]
	v_pk_mov_b32 v[68:69], v[66:67], v[52:53] op_sel:[1,0]
	v_mov_b32_e32 v67, v53
	v_pk_add_f32 v[52:53], v[68:69], v[66:67]
	v_fma_mix_f32 v67, v59, s65, v50 op_sel:[0,0,1] op_sel_hi:[0,0,1]
	v_fma_mix_f32 v66, v59, s65, v50 op_sel_hi:[0,0,1]
	v_fma_mix_f32 v69, v59, s65, v51 op_sel:[0,0,1] op_sel_hi:[0,0,1]
	v_fma_mix_f32 v68, v59, s65, v51 op_sel_hi:[0,0,1]
	v_pk_mul_f32 v[50:51], v[68:69], v[68:69]
	v_pk_mul_f32 v[70:71], v[66:67], v[66:67]
	v_pk_add_f32 v[52:53], v[52:53], v[52:53] op_sel_hi:[0,1]
	v_pk_mov_b32 v[72:73], v[70:71], v[50:51] op_sel:[1,0]
	v_mov_b32_e32 v71, v51
	v_pk_add_f32 v[50:51], v[72:73], v[70:71]
	v_fma_mix_f32 v70, v59, s65, v48 op_sel_hi:[0,0,1]
	v_fma_mix_f32 v71, v59, s65, v48 op_sel:[0,0,1] op_sel_hi:[0,0,1]
	v_mul_f32_e32 v48, v70, v70
	v_fma_mix_f32 v73, v59, s65, v49 op_sel:[0,0,1] op_sel_hi:[0,0,1]
	v_fma_mix_f32 v72, v59, s65, v49 op_sel_hi:[0,0,1]
	v_pk_fma_f32 v[48:49], v[70:71], v[70:71], v[48:49] op_sel_hi:[1,1,0]
	v_pk_add_f32 v[50:51], v[50:51], v[50:51] op_sel_hi:[0,1]
	v_mul_f32_e32 v48, v72, v72
	v_pk_fma_f32 v[74:75], v[72:73], v[72:73], v[48:49] op_sel_hi:[1,1,0]
	v_fma_mix_f32 v76, v59, s65, v47 op_sel_hi:[0,0,1]
	v_fma_mix_f32 v47, v59, s65, v46 op_sel:[0,0,1] op_sel_hi:[0,0,1]
	v_fma_mix_f32 v46, v59, s65, v46 op_sel_hi:[0,0,1]
	v_mul_f32_e32 v48, v46, v46
	v_mul_f32_e32 v74, v47, v47
	v_mul_f32_e32 v52, v76, v76
	v_mul_f32_e32 v50, v77, v77
; DI unsigned pk_bf16(float lo, float hi) { f32x2_t v = {lo, hi}; return __builtin_bit_cast(unsigned, __builtin_convertvector(v, bf16x2_t)); }
; DI float shfl_xor_l(float v, int mask, int lane) { return __int_as_float(__builtin_amdgcn_ds_bpermute((lane ^ mask) << 2, __float_as_int(v))); }
; DI void ln_phase(const Params& p, const u16* src, const float* g, const float* b, float* dstf, u16* dstb) {
;     ...
;     for (int i = 0; i < 4; ++i) { v[i] = v[i] - mu; q += (v[i][0] * v[i][0] + v[i][1] * v[i][1]) + (v[i][2] * v[i][2] + v[i][3] * v[i][3]); }
; #pragma unroll
;     for (int o = 32; o >= 1; o >>= 1) q += shfl_xor_l(q, o, lane);
;     const float rstd = 1.0f / sqrtf(q * (1.0f / 1024.0f) + 1e-5f);
; #pragma unroll
;     for (int i = 0; i < 4; ++i) {
;       const int col = i * 256 + lane * 4;
;       const f32x4 o = v[i] * rstd * gv[i] + bv[i];
;       if (dstf) *(f32x4*)(dstf + (size_t)row * D + col) = o;
;       if (dstb) { u32x2 ob; ob[0] = pk_bf16(o[0], o[1]); ob[1] = pk_bf16(o[2], o[3]); *(u32x2*)(dstb + (size_t)row * D + col) = ob; }
;     }
; #pragma unroll
;     for (int i = 0; i < 4; ++i) raw[i] = nxt[i];
;   }
	v_pk_add_f32 v[48:49], v[48:49], v[74:75]
	v_pk_add_f32 v[50:51], v[52:53], v[50:51]
	s_nop 0
	v_pk_add_f32 v[48:49], v[48:49], v[50:51]
	s_nop 0
	v_add_f32_e32 v48, v48, v49
	s_nop 1
	v_add_f32_dpp v48, v48, v48 quad_perm:[1,0,3,2] row_mask:0xf bank_mask:0xf
	s_nop 1
	v_add_f32_dpp v48, v48, v48 quad_perm:[2,3,0,1] row_mask:0xf bank_mask:0xf
	s_nop 1
	v_add_f32_dpp v48, v48, v48 row_half_mirror row_mask:0xf bank_mask:0xf
	s_nop 1
	v_add_f32_dpp v48, v48, v48 row_mirror row_mask:0xf bank_mask:0xf
	v_mov_b32_e32 v49, v48
	s_nop 1
	v_permlane16_swap_b32 v49, v48
	v_add_f32_e32 v48, v48, v49
	v_mov_b32_e32 v49, v48
	s_nop 1
	v_permlane32_swap_b32 v49, v48
	v_add_f32_e32 v48, v48, v49
	v_mov_b32_e32 v49, 0x3727c5ac
	v_fmamk_f32 v48, v48, 0x3a800000, v49
	v_cmp_gt_f32_e32 vcc, s66, v48
	v_mul_f32_e32 v49, 0x4f800000, v48
	s_nop 0
	v_cndmask_b32_e32 v48, v48, v49, vcc
	v_sqrt_f32_e32 v49, v48
	s_nop 0
	v_add_u32_e32 v50, -1, v49
	v_fma_f32 v51, -v50, v49, v48
	v_cmp_ge_f32_e64 s[38:39], 0, v51
	v_add_u32_e32 v51, 1, v49
	s_nop 0
	v_cndmask_b32_e64 v50, v49, v50, s[38:39]
	v_fma_f32 v49, -v51, v49, v48
	v_cmp_lt_f32_e64 s[38:39], 0, v49
	s_nop 1
	v_cndmask_b32_e64 v49, v50, v51, s[38:39]
	v_mul_f32_e32 v50, 0x37800000, v49
	v_cndmask_b32_e32 v49, v49, v50, vcc
	v_mov_b32_e32 v50, 0x260
	v_cmp_class_f32_e32 vcc, v48, v50
	s_nop 1
	v_cndmask_b32_e32 v48, v49, v48, vcc
	v_div_scale_f32 v49, s[2:3], v48, v48, 1.0
	v_rcp_f32_e32 v50, v49
	s_mov_b32 s2, 0xaa80000
	v_fma_f32 v51, -v49, v50, 1.0
	v_fmac_f32_e32 v50, v51, v50
	v_div_scale_f32 v51, vcc, 1.0, v48, 1.0
	v_mul_f32_e32 v52, v51, v50
	v_fma_f32 v53, -v49, v52, v51
	v_fmac_f32_e32 v52, v53, v50
	v_fma_f32 v49, -v49, v52, v51
	v_div_fmas_f32 v49, v49, v50, v52
	v_div_fixup_f32 v48, v49, v48, 1.0
	v_pk_mul_f32 v[50:51], v[60:61], v[48:49] op_sel_hi:[1,0]
	v_pk_mul_f32 v[52:53], v[62:63], v[48:49] op_sel_hi:[1,0]
	v_pk_fma_f32 v[50:51], v[0:1], v[50:51], v[8:9]
	v_pk_fma_f32 v[52:53], v[2:3], v[52:53], v[10:11]
	v_cvt_pk_bf16_f32 v50, v50, v51
	v_cvt_pk_bf16_f32 v51, v52, v53
	v_lshl_add_u64 v[52:53], v[34:35], 0, v[64:65]
	v_add_co_u32_e32 v52, vcc, s2, v52
	v_pk_mul_f32 v[60:61], v[68:69], v[48:49] op_sel_hi:[1,0]
	s_nop 0
	v_addc_co_u32_e32 v53, vcc, 0, v53, vcc
	global_store_dwordx2 v[52:53], v[50:51], off
	v_pk_mul_f32 v[50:51], v[66:67], v[48:49] op_sel_hi:[1,0]
	v_pk_fma_f32 v[60:61], v[6:7], v[60:61], v[14:15]
	v_pk_fma_f32 v[50:51], v[4:5], v[50:51], v[12:13]
	v_pk_mul_f32 v[46:47], v[46:47], v[48:49] op_sel_hi:[1,0]
	v_cvt_pk_bf16_f32 v50, v50, v51
	v_cvt_pk_bf16_f32 v51, v60, v61
	global_store_dwordx2 v[52:53], v[50:51], off offset:512
	v_pk_mul_f32 v[50:51], v[70:71], v[48:49] op_sel_hi:[1,0]
	v_pk_mul_f32 v[60:61], v[72:73], v[48:49] op_sel_hi:[1,0]
	v_pk_mul_f32 v[48:49], v[76:77], v[48:49] op_sel_hi:[1,0]
	v_pk_fma_f32 v[60:61], v[18:19], v[60:61], v[26:27]
	v_pk_fma_f32 v[50:51], v[16:17], v[50:51], v[24:25]
	v_pk_fma_f32 v[48:49], v[22:23], v[48:49], v[30:31]
	v_pk_fma_f32 v[46:47], v[20:21], v[46:47], v[28:29]
	v_readlane_b32 s2, v255, 14
	v_cvt_pk_bf16_f32 v50, v50, v51
	v_cvt_pk_bf16_f32 v51, v60, v61
	v_cvt_pk_bf16_f32 v46, v46, v47
	v_cvt_pk_bf16_f32 v47, v48, v49
	v_readlane_b32 s3, v255, 15
	global_store_dwordx2 v[52:53], v[50:51], off offset:1024
	global_store_dwordx2 v[52:53], v[46:47], off offset:1536
	v_lshl_add_u64 v[34:35], v[34:35], 0, s[2:3]
	v_lshl_add_u64 v[36:37], v[36:37], 0, s[2:3]
	s_andn2_b64 exec, exec, s[22:23]
	s_cbranch_execz .LBB0_1114
.LBB0_1112:
	v_readlane_b32 s2, v255, 16
	v_readlane_b32 s3, v255, 17
	s_nop 0
	v_add_u32_e32 v32, s2, v32
	s_movk_i32 s2, 0x4000
	v_cmp_gt_i32_e32 vcc, s2, v32
	v_cmp_lt_i32_e64 s[38:39], s64, v32
	s_and_saveexec_b64 s[28:29], vcc
	s_cbranch_execz .LBB0_1111
	v_lshl_add_u64 v[38:39], v[36:37], 0, v[64:65]
	v_add_co_u32_e32 v44, vcc, 0x8a00000, v38
	s_nop 1
	v_addc_co_u32_e32 v45, vcc, 0, v39, vcc
	s_nop 0
	s_branch .LBB0_1111

; DI float h2lo(unsigned u) { return (float)__builtin_bit_cast(f16x2_t, u)[0]; }
; DI float h2hi(unsigned u) { return (float)__builtin_bit_cast(f16x2_t, u)[1]; }
; DI int my_tid() { int t = tid_raw(); asm volatile("" : "+v"(t)); return t; }
; DI float shfl_xor_l(float v, int mask, int lane) { return __int_as_float(__builtin_amdgcn_ds_bpermute((lane ^ mask) << 2, __float_as_int(v))); }
; DI void ln_phase(const Params& p, const u16* src, const float* g, const float* b, float* dstf, u16* dstb) {
;   const int lane = my_tid() & 63, wid = my_tid() >> 6;
;   const int stride = gridDim.x * 8;
;   int row = blockIdx.x * 8 + wid;
;   u32x2 raw[4], nxt[4];
;   f32x4 gv[4], bv[4];
; #pragma unroll
;   for (int i = 0; i < 4; ++i) { gv[i] = *(const f32x4*)(g + i * 256 + lane * 4); bv[i] = *(const f32x4*)(b + i * 256 + lane * 4); }
;   if (row < S) {
; #pragma unroll
;     for (int i = 0; i < 4; ++i) raw[i] = *(const u32x2*)(src + (size_t)row * D + i * 256 + lane * 4);
;   }
;   for (; row < S; row += stride) {
;     const int rn = row + stride;
;     if (rn < S) {
; #pragma unroll
;       for (int i = 0; i < 4; ++i) nxt[i] = *(const u32x2*)(src + (size_t)rn * D + i * 256 + lane * 4);
;     }
;     f32x4 v[4];
;     float s = 0.f;
; #pragma unroll
;     for (int i = 0; i < 4; ++i) { v[i] = (f32x4){h2lo(raw[i][0]), h2hi(raw[i][0]), h2lo(raw[i][1]), h2hi(raw[i][1])}; s += (v[i][0] + v[i][1]) + (v[i][2] + v[i][3]); }
; #pragma unroll
;     for (int o = 32; o >= 1; o >>= 1) s += shfl_xor_l(s, o, lane);
.LBB0_1322:
	s_or_b64 exec, exec, s[8:9]
	s_waitcnt lgkmcnt(0)
	s_barrier
	s_getreg_b32 s2, hwreg(HW_REG_HW_ID, 0, 6)
	s_lshl_b32 s2, s2, 2
	s_and_b32 s2, s2, 0xfc
	s_add_i32 s2, s2, 0x20040
	v_mov_b32_e32 v0, s2
	ds_read_b32 v0, v0
	s_waitcnt lgkmcnt(0)
	v_readfirstlane_b32 s2, v0
	s_nop 1
	v_lshl_or_b32 v38, s2, 6, v214
	s_getreg_b32 s2, hwreg(HW_REG_HW_ID, 0, 6)
	s_lshl_b32 s2, s2, 2
	s_and_b32 s2, s2, 0xfc
	s_add_i32 s2, s2, 0x20040
	v_mov_b32_e32 v0, s2
	ds_read_b32 v0, v0
	s_waitcnt lgkmcnt(0)
	v_readfirstlane_b32 s2, v0
	s_nop 1
	v_lshl_or_b32 v0, s2, 6, v214
	v_readlane_b32 s2, v255, 12
	v_ashrrev_i32_e32 v39, 6, v0
	s_nop 0
	v_add_u32_e32 v36, s2, v39
	s_movk_i32 s2, 0x4000
	v_cmp_gt_i32_e32 vcc, s2, v36
	s_and_saveexec_b64 s[8:9], vcc
	s_cbranch_execz .LBB0_1343
	s_lshl_b64 s[2:3], s[92:93], 2
	s_add_u32 s22, s84, s2
	s_addc_u32 s23, s85, s3
	v_lshlrev_b32_e32 v42, 2, v38
	s_add_u32 s2, s86, s2
	v_and_b32_e32 v34, 0xfc, v42
	s_addc_u32 s3, s87, s3
	v_lshlrev_b32_e32 v28, 2, v34
	global_load_dwordx4 v[0:3], v28, s[22:23]
	global_load_dwordx4 v[4:7], v28, s[22:23] offset:1024
	global_load_dwordx4 v[8:11], v28, s[2:3]
	global_load_dwordx4 v[12:15], v28, s[2:3] offset:1024
	global_load_dwordx4 v[16:19], v28, s[22:23] offset:2048
	global_load_dwordx4 v[20:23], v28, s[22:23] offset:3072
	global_load_dwordx4 v[24:27], v28, s[2:3] offset:2048
	s_nop 0
	global_load_dwordx4 v[28:31], v28, s[2:3] offset:3072
	v_ashrrev_i32_e32 v37, 31, v36
	v_readlane_b32 s2, v254, 20
	v_lshlrev_b64 v[40:41], 11, v[36:37]
	v_readlane_b32 s3, v254, 21
	v_lshlrev_b32_e32 v64, 1, v34
	s_movk_i32 s7, 0x80
	v_lshl_add_u64 v[32:33], s[2:3], 0, v[40:41]
	v_lshl_add_u64 v[32:33], v[32:33], 0, v[64:65]
	v_lshl_add_u64 v[90:91], v[32:33], 0, v[64:65]
	v_readfirstlane_b32 s100, v39
	v_readlane_b32 s101, v255, 14
	s_lshl_b32 s100, s100, 14
	s_nop 0
	v_mov_b32_e32 v94, s101
	v_readlane_b32 s101, v255, 15
	v_add_u32_e32 v92, s100, v64
	s_nop 1
	v_mov_b32_e32 v95, s101
	s_mov_b32 m0, s100
	s_nop 0
	global_load_lds_dwordx4 v[90:91], off
	global_load_lds_dwordx4 v[90:91], off offset:1024
	v_lshl_add_u64 v[90:91], v[90:91], 0, v[94:95]
	s_add_u32 s100, s100, 0x800
	s_mov_b32 m0, s100
	s_nop 0
	global_load_lds_dwordx4 v[90:91], off
	global_load_lds_dwordx4 v[90:91], off offset:1024
	v_lshl_add_u64 v[90:91], v[90:91], 0, v[94:95]
	s_add_u32 s100, s100, 0x800
	s_mov_b32 m0, s100
	s_nop 0
	global_load_lds_dwordx4 v[90:91], off
	global_load_lds_dwordx4 v[90:91], off offset:1024
	v_lshl_add_u64 v[90:91], v[90:91], 0, v[94:95]
	s_add_u32 s100, s100, 0x800
	s_mov_b32 m0, s100
	s_nop 0
	global_load_lds_dwordx4 v[90:91], off
	global_load_lds_dwordx4 v[90:91], off offset:1024
	v_lshl_add_u64 v[90:91], v[90:91], 0, v[94:95]
	s_add_u32 s100, s100, 0x800
	s_mov_b32 m0, s100
	s_nop 0
	global_load_lds_dwordx4 v[90:91], off
	global_load_lds_dwordx4 v[90:91], off offset:1024
	v_lshl_add_u64 v[90:91], v[90:91], 0, v[94:95]
	s_add_u32 s100, s100, 0x800
	s_mov_b32 m0, s100
	s_nop 0
	global_load_lds_dwordx4 v[90:91], off
	global_load_lds_dwordx4 v[90:91], off offset:1024
	v_lshl_add_u64 v[90:91], v[90:91], 0, v[94:95]
	s_add_u32 s100, s100, 0x800
	s_mov_b32 m0, s100
	s_nop 0
	global_load_lds_dwordx4 v[90:91], off
	global_load_lds_dwordx4 v[90:91], off offset:1024
	v_lshl_add_u64 v[90:91], v[90:91], 0, v[94:95]
	s_add_u32 s100, s100, 0x800
	s_mov_b32 m0, s100
	s_nop 0
	global_load_lds_dwordx4 v[90:91], off
	global_load_lds_dwordx4 v[90:91], off offset:1024
	s_nop 0
	s_and_b64 s[2:3], s[46:47], exec
	v_bfrev_b32_e32 v43, 0.5
	v_readlane_b32 s2, v254, 22
	v_bitop3_b32 v70, v42, s7, v43 bitop3:0x6c
	v_readlane_b32 s7, v255, 13
	v_readlane_b32 s3, v254, 23
	v_readlane_b32 s36, v255, 29
	v_bitop3_b32 v71, v42, 64, v43 bitop3:0x6c
	v_bitop3_b32 v72, v42, 32, v43 bitop3:0x6c
	v_bitop3_b32 v73, v42, 16, v43 bitop3:0x6c
	v_bitop3_b32 v74, v42, 8, v43 bitop3:0x6c
	v_bitop3_b32 v75, v42, 4, v43 bitop3:0x6c
	v_and_b32_e32 v44, 63, v38
	v_add_u32_e32 v38, s7, v39
	v_lshlrev_b64 v[42:43], 12, v[36:37]
	s_cselect_b32 s3, s3, 0
	s_cselect_b32 s2, s2, 0
	v_readlane_b32 s37, v255, 30
	v_ashrrev_i32_e32 v39, 31, v38
	v_lshl_or_b32 v42, v44, 4, v42
	s_cmp_lg_u64 s[36:37], 0
	v_lshlrev_b32_e32 v64, 3, v44
	v_lshlrev_b64 v[38:39], 11, v[38:39]
	v_lshl_add_u64 v[40:41], s[2:3], 0, v[40:41]
	v_lshl_add_u64 v[42:43], s[36:37], 0, v[42:43]
	s_mov_b64 s[2:3], 0x800
	v_mov_b32_e32 v44, 0
	s_mov_b64 s[22:23], 0
	s_cselect_b64 s[28:29], -1, 0
	v_lshl_add_u64 v[38:39], s[90:91], 0, v[38:39]
	v_lshl_add_u64 v[42:43], v[42:43], 0, s[2:3]
	v_mov_b32_e32 v45, v44
	v_mov_b32_e32 v46, v44
	v_mov_b32_e32 v47, v44
	v_mov_b32_e32 v48, v44
	v_mov_b32_e32 v49, v44
	v_mov_b32_e32 v50, v44
	v_mov_b32_e32 v51, v44
	s_waitcnt vmcnt(0)
	s_branch .LBB0_1325
.LBB0_1324:
	s_and_b64 s[2:3], exec, s[36:37]
	s_or_b64 s[22:23], s[2:3], s[22:23]
	v_readlane_b32 s2, v255, 14
	v_readlane_b32 s3, v255, 15
	v_readlane_b32 s40, v255, 40
	v_lshl_add_u64 v[38:39], v[38:39], 0, s[2:3]
	v_lshl_add_u64 v[40:41], v[40:41], 0, s[2:3]
	v_readlane_b32 s2, v255, 18
	v_readlane_b32 s3, v255, 19
	v_lshl_add_u64 v[42:43], v[42:43], 0, s[2:3]
	v_readlane_b32 s41, v255, 41
	s_andn2_b64 exec, exec, s[22:23]
	s_cbranch_execz .LBB0_1343
.LBB0_1325:
	v_readlane_b32 s2, v255, 16
	v_readlane_b32 s3, v255, 17
	s_nop 0
	v_add_u32_e32 v36, s2, v36
	s_movk_i32 s2, 0x4000
	v_cmp_gt_i32_e32 vcc, s2, v36
	v_cmp_lt_i32_e64 s[36:37], s64, v36
	s_and_saveexec_b64 s[38:39], vcc
	s_cbranch_execz .LBB0_1327
	v_lshl_add_u64 v[44:45], v[38:39], 0, v[64:65]
	v_add_co_u32_e32 v50, vcc, 0xd280000, v44
	s_nop 1
	v_addc_co_u32_e32 v51, vcc, 0, v45, vcc
	s_nop 0
; DI float h2lo(unsigned u) { return (float)__builtin_bit_cast(f16x2_t, u)[0]; }
; DI float h2hi(unsigned u) { return (float)__builtin_bit_cast(f16x2_t, u)[1]; }
; DI float shfl_xor_l(float v, int mask, int lane) { return __int_as_float(__builtin_amdgcn_ds_bpermute((lane ^ mask) << 2, __float_as_int(v))); }
; DI void ln_phase(const Params& p, const u16* src, const float* g, const float* b, float* dstf, u16* dstb) {
;     ...
;     f32x4 v[4];
;     float s = 0.f;
; #pragma unroll
;     for (int i = 0; i < 4; ++i) { v[i] = (f32x4){h2lo(raw[i][0]), h2hi(raw[i][0]), h2lo(raw[i][1]), h2hi(raw[i][1])}; s += (v[i][0] + v[i][1]) + (v[i][2] + v[i][3]); }
; #pragma unroll
;     for (int o = 32; o >= 1; o >>= 1) s += shfl_xor_l(s, o, lane);
;     const float mu = s * (1.0f / 1024.0f);
;     float q = 0.f;
; #pragma unroll
;     for (int i = 0; i < 4; ++i) { v[i] = v[i] - mu; q += (v[i][0] * v[i][0] + v[i][1] * v[i][1]) + (v[i][2] * v[i][2] + v[i][3] * v[i][3]); }
; #pragma unroll
;     for (int o = 32; o >= 1; o >>= 1) q += shfl_xor_l(q, o, lane);
;     const float rstd = 1.0f / sqrtf(q * (1.0f / 1024.0f) + 1e-5f);
; #pragma unroll
;     for (int i = 0; i < 4; ++i) {
;       const int col = i * 256 + lane * 4;
;       const f32x4 o = v[i] * rstd * gv[i] + bv[i];
;       if (dstf) *(f32x4*)(dstf + (size_t)row * D + col) = o;
.LBB0_1327:
	s_or_b64 exec, exec, s[38:39]
	ds_read_b64 v[54:55], v92
	ds_read_b64 v[52:53], v92 offset:512
	ds_read_b64 v[34:35], v92 offset:1024
	ds_read_b64 v[32:33], v92 offset:1536
	v_add_u32_e32 v92, 0x800, v92
	s_waitcnt lgkmcnt(0)
	v_cvt_f32_f16_sdwa v56, v54 dst_sel:DWORD dst_unused:UNUSED_PAD src0_sel:WORD_1
	v_cvt_f32_f16_e32 v58, v54
	v_cvt_f32_f16_sdwa v57, v55 dst_sel:DWORD dst_unused:UNUSED_PAD src0_sel:WORD_1
	v_cvt_f32_f16_e32 v59, v55
	v_cvt_f32_f16_sdwa v60, v52 dst_sel:DWORD dst_unused:UNUSED_PAD src0_sel:WORD_1
	v_cvt_f32_f16_e32 v62, v52
	v_cvt_f32_f16_sdwa v61, v53 dst_sel:DWORD dst_unused:UNUSED_PAD src0_sel:WORD_1
	v_cvt_f32_f16_e32 v63, v53
	v_pk_add_f32 v[56:57], v[58:59], v[56:57]
	v_cvt_f32_f16_sdwa v66, v35 dst_sel:DWORD dst_unused:UNUSED_PAD src0_sel:WORD_1
	v_add_f32_e32 v37, v56, v57
	v_pk_add_f32 v[58:59], v[62:63], v[60:61]
	v_add_f32_e32 v57, 0, v37
	v_pk_add_f32 v[58:59], v[58:59], v[58:59] op_sel_hi:[0,1]
	v_cvt_f32_f16_sdwa v37, v34 dst_sel:DWORD dst_unused:UNUSED_PAD src0_sel:WORD_1
	v_cvt_f32_f16_e32 v61, v34
	v_cvt_f32_f16_e32 v67, v35
	v_cvt_f32_f16_sdwa v60, v32 dst_sel:DWORD dst_unused:UNUSED_PAD src0_sel:WORD_1
	v_cvt_f32_f16_e32 v62, v32
	v_cvt_f32_f16_sdwa v56, v33 dst_sel:DWORD dst_unused:UNUSED_PAD src0_sel:WORD_1
	v_cvt_f32_f16_e32 v58, v33
	v_add_f32_e32 v63, v61, v37
	v_add_f32_e32 v61, v67, v66
	v_pk_add_f32 v[60:61], v[62:63], v[60:61]
	v_pk_add_f32 v[56:57], v[58:59], v[56:57]
	s_nop 0
	v_pk_add_f32 v[56:57], v[60:61], v[56:57]
	s_nop 0
	v_add_f32_e32 v37, v56, v57
	s_nop 1
	v_add_f32_dpp v37, v37, v37 quad_perm:[1,0,3,2] row_mask:0xf bank_mask:0xf
	s_nop 1
	v_add_f32_dpp v37, v37, v37 quad_perm:[2,3,0,1] row_mask:0xf bank_mask:0xf
	s_nop 1
	v_add_f32_dpp v37, v37, v37 row_half_mirror row_mask:0xf bank_mask:0xf
	s_nop 1
	v_add_f32_dpp v37, v37, v37 row_mirror row_mask:0xf bank_mask:0xf
	v_mov_b32_e32 v56, v37
	s_nop 1
	v_permlane16_swap_b32 v56, v37
	v_add_f32_e32 v37, v37, v56
	v_mov_b32_e32 v56, v37
	s_nop 1
	v_permlane32_swap_b32 v56, v37
	v_add_f32_e32 v37, v37, v56
	v_fma_mix_f32 v67, v37, s65, v54 op_sel:[0,0,1] op_sel_hi:[0,0,1]
	v_fma_mix_f32 v66, v37, s65, v54 op_sel_hi:[0,0,1]
	v_fma_mix_f32 v77, v37, s65, v55 op_sel:[0,0,1] op_sel_hi:[0,0,1]
	v_fma_mix_f32 v76, v37, s65, v55 op_sel_hi:[0,0,1]
	v_fma_mix_f32 v61, v37, s65, v53 op_sel:[0,0,1] op_sel_hi:[0,0,1]
	v_fma_mix_f32 v60, v37, s65, v53 op_sel_hi:[0,0,1]
	v_fma_mix_f32 v63, v37, s65, v52 op_sel:[0,0,1] op_sel_hi:[0,0,1]
	v_fma_mix_f32 v62, v37, s65, v52 op_sel_hi:[0,0,1]
	v_pk_mul_f32 v[52:53], v[76:77], v[76:77]
	v_pk_mul_f32 v[54:55], v[66:67], v[66:67]
	v_pk_mul_f32 v[56:57], v[60:61], v[60:61]
	v_pk_mov_b32 v[58:59], v[54:55], v[52:53] op_sel:[1,0]
	v_mov_b32_e32 v55, v53
	v_pk_add_f32 v[52:53], v[58:59], v[54:55]
	v_fma_mix_f32 v58, v37, s65, v34 op_sel_hi:[0,0,1]
	v_pk_add_f32 v[68:69], v[52:53], v[52:53] op_sel_hi:[0,1]
	v_pk_mul_f32 v[52:53], v[62:63], v[62:63]
	v_fma_mix_f32 v59, v37, s65, v34 op_sel:[0,0,1] op_sel_hi:[0,0,1]
	v_mul_f32_e32 v34, v58, v58
	v_pk_mov_b32 v[54:55], v[52:53], v[56:57] op_sel:[1,0]
	v_mov_b32_e32 v53, v57
	v_fma_mix_f32 v57, v37, s65, v35 op_sel:[0,0,1] op_sel_hi:[0,0,1]
	v_fma_mix_f32 v56, v37, s65, v35 op_sel_hi:[0,0,1]
	v_pk_fma_f32 v[34:35], v[58:59], v[58:59], v[34:35] op_sel_hi:[1,1,0]
	v_pk_add_f32 v[52:53], v[54:55], v[52:53]
	v_mul_f32_e32 v34, v56, v56
	v_pk_add_f32 v[78:79], v[52:53], v[52:53] op_sel_hi:[0,1]
	v_pk_fma_f32 v[80:81], v[56:57], v[56:57], v[34:35] op_sel_hi:[1,1,0]
	v_fma_mix_f32 v53, v37, s65, v33 op_sel:[0,0,1] op_sel_hi:[0,0,1]
	v_fma_mix_f32 v52, v37, s65, v33 op_sel_hi:[0,0,1]
	v_fma_mix_f32 v55, v37, s65, v32 op_sel:[0,0,1] op_sel_hi:[0,0,1]
	v_fma_mix_f32 v54, v37, s65, v32 op_sel_hi:[0,0,1]
	v_mul_f32_e32 v34, v54, v54
	v_mul_f32_e32 v80, v55, v55
	v_mul_f32_e32 v68, v52, v52
	v_mul_f32_e32 v78, v53, v53
	v_pk_add_f32 v[32:33], v[34:35], v[80:81]
	v_pk_add_f32 v[34:35], v[68:69], v[78:79]
	s_nop 0
	v_pk_add_f32 v[32:33], v[32:33], v[34:35]
	s_nop 0
	v_add_f32_e32 v32, v32, v33
	s_nop 1
	v_add_f32_dpp v32, v32, v32 quad_perm:[1,0,3,2] row_mask:0xf bank_mask:0xf
	s_nop 1
	v_add_f32_dpp v32, v32, v32 quad_perm:[2,3,0,1] row_mask:0xf bank_mask:0xf
	s_nop 1
	v_add_f32_dpp v32, v32, v32 row_half_mirror row_mask:0xf bank_mask:0xf
	s_nop 1
	v_add_f32_dpp v32, v32, v32 row_mirror row_mask:0xf bank_mask:0xf
	v_mov_b32_e32 v33, v32
	s_nop 1
	v_permlane16_swap_b32 v33, v32
	v_add_f32_e32 v32, v32, v33
	v_mov_b32_e32 v33, v32
	s_nop 1
	v_permlane32_swap_b32 v33, v32
	v_add_f32_e32 v32, v32, v33
	v_mov_b32_e32 v33, 0x3727c5ac
	v_fmamk_f32 v32, v32, 0x3a800000, v33
	v_mul_f32_e32 v33, 0x4f800000, v32
	v_cmp_gt_f32_e32 vcc, s66, v32
	s_nop 1
	v_cndmask_b32_e32 v32, v32, v33, vcc
	v_sqrt_f32_e32 v33, v32
	s_nop 0
	v_add_u32_e32 v34, -1, v33
	v_add_u32_e32 v35, 1, v33
	v_fma_f32 v37, -v34, v33, v32
	v_fma_f32 v68, -v35, v33, v32
	v_cmp_ge_f32_e64 s[38:39], 0, v37
	s_nop 1
	v_cndmask_b32_e64 v33, v33, v34, s[38:39]
	v_cmp_lt_f32_e64 s[38:39], 0, v68
	s_nop 1
	v_cndmask_b32_e64 v33, v33, v35, s[38:39]
	v_mul_f32_e32 v34, 0x37800000, v33
	v_cndmask_b32_e32 v33, v33, v34, vcc
	v_mov_b32_e32 v34, 0x260
	v_cmp_class_f32_e32 vcc, v32, v34
	s_nop 1
	v_cndmask_b32_e32 v32, v33, v32, vcc
	v_div_scale_f32 v33, s[2:3], v32, v32, 1.0
	v_rcp_f32_e32 v34, v33
	v_div_scale_f32 v35, vcc, 1.0, v32, 1.0
	v_fma_f32 v37, -v33, v34, 1.0
	v_fmac_f32_e32 v34, v37, v34
	v_mul_f32_e32 v37, v35, v34
	v_fma_f32 v68, -v33, v37, v35
	v_fmac_f32_e32 v37, v68, v34
	v_fma_f32 v33, -v33, v37, v35
	v_div_fmas_f32 v33, v33, v34, v37
	v_div_fixup_f32 v68, v33, v32, 1.0
	v_pk_mul_f32 v[32:33], v[66:67], v[68:69] op_sel_hi:[1,0]
	v_pk_mul_f32 v[34:35], v[76:77], v[68:69] op_sel_hi:[1,0]
	v_cndmask_b32_e64 v37, 0, 1, s[28:29]
	v_pk_fma_f32 v[34:35], v[2:3], v[34:35], v[10:11]
	v_cmp_ne_u32_e64 s[38:39], 1, v37
	s_andn2_b64 vcc, exec, s[28:29]
	v_pk_fma_f32 v[32:33], v[0:1], v[32:33], v[8:9]
	s_cbranch_vccnz .LBB0_1329
	global_store_dwordx4 v[42:43], v[32:35], off offset:-2048
